# speedup vs baseline: 1.0164x; 1.0164x over previous
; __global__ void __launch_bounds__(NTHREADS, 2) fwd_megakernel(Params p_arg) {
;     ...
;   if (xb.local_ok) {
; #pragma unroll 1
;     for (int i = 0; i < (int)xb.x * XCC_SKEW_SLEEPS; ++i) __builtin_amdgcn_s_sleep(127);
;   }
.LBB0_110:
	s_or_b64 exec, exec, s[4:5]
	s_cmpk_gt_u32 s16, 0xffff
	s_cselect_b64 s[4:5], -1, 0
	s_cmp_gt_i32 s7, 0
	s_cselect_b64 s[0:1], -1, 0
	v_writelane_b32 v255, s4, 16
	s_and_b64 s[0:1], s[4:5], s[0:1]
	s_mov_b32 s29, 0
	v_writelane_b32 v255, s5, 17
	s_and_b64 vcc, exec, s[0:1]
	s_barrier
	s_cbranch_vccz .LBB0_113
	s_lshl_b32 s0, s7, 1
	s_max_i32 s0, s0, 1

.LBB0_120:
	global_load_dwordx4 v[54:57], v[24:25], off offset:-2048
	global_load_dwordx4 v[58:61], v[24:25], off offset:-1024
	global_load_dwordx4 v[62:65], v[24:25], off
	global_load_dwordx4 v[66:69], v[24:25], off offset:1024
	v_lshl_add_u64 v[70:71], v[26:27], 0, s[6:7]
	s_add_u32 s6, s6, 0x800
	s_addc_u32 s7, s7, 0
	s_cmpk_eq_u32 s6, 0x8000
	v_lshl_add_u64 v[24:25], v[24:25], 0, s[48:49]
	s_waitcnt vmcnt(3)
	v_mov_b32_e32 v80, v55
	s_waitcnt vmcnt(2)
	v_mov_b32_e32 v81, v59
	v_mov_b32_e32 v78, v54
	v_mov_b32_e32 v79, v58
	v_pk_mul_f32 v[80:81], v[80:81], v[80:81]
	v_mov_b32_e32 v74, v56
	v_mov_b32_e32 v75, v60
	v_pk_fma_f32 v[78:79], v[78:79], v[78:79], v[80:81]
	v_mov_b32_e32 v76, v57
	v_mov_b32_e32 v77, v61
	v_pk_fma_f32 v[74:75], v[74:75], v[74:75], v[78:79]
	s_nop 0
	v_pk_fma_f32 v[72:73], v[76:77], v[76:77], v[74:75]
	s_nop 0
	v_add_f32_e32 v53, v72, v73
	s_waitcnt vmcnt(1)
	v_mov_b32_e32 v80, v63
	s_waitcnt vmcnt(0)
	v_mov_b32_e32 v81, v67
	v_mov_b32_e32 v78, v62
	v_mov_b32_e32 v79, v66
	v_pk_mul_f32 v[80:81], v[80:81], v[80:81]
	v_mov_b32_e32 v74, v64
	v_mov_b32_e32 v75, v68
	v_pk_fma_f32 v[78:79], v[78:79], v[78:79], v[80:81]
	v_mov_b32_e32 v76, v65
	v_mov_b32_e32 v77, v69
	v_pk_fma_f32 v[74:75], v[74:75], v[74:75], v[78:79]
	s_nop 0
	v_pk_fma_f32 v[74:75], v[76:77], v[76:77], v[74:75]
	s_nop 0
	v_add_f32_e32 v53, v53, v74
	v_add_f32_e32 v53, v53, v75
	ds_bpermute_b32 v72, v44, v53
	s_waitcnt lgkmcnt(0)
	v_add_f32_e32 v53, v53, v72
	ds_bpermute_b32 v72, v45, v53
	s_waitcnt lgkmcnt(0)
	v_add_f32_e32 v53, v53, v72
	ds_bpermute_b32 v72, v46, v53
	s_waitcnt lgkmcnt(0)
	v_add_f32_e32 v53, v53, v72
	ds_bpermute_b32 v72, v47, v53
	s_waitcnt lgkmcnt(0)
	v_add_f32_e32 v53, v53, v72
	ds_bpermute_b32 v72, v48, v53
	s_waitcnt lgkmcnt(0)
	v_add_f32_e32 v53, v53, v72
	ds_bpermute_b32 v72, v49, v53
	s_waitcnt lgkmcnt(0)
	v_add_f32_e32 v53, v53, v72
	v_fmamk_f32 v53, v53, 0x3a800000, v149
	v_cmp_gt_f32_e32 vcc, s26, v53
	v_mul_f32_e32 v72, 0x4b800000, v53
	s_nop 0
	v_cndmask_b32_e32 v53, v53, v72, vcc
	v_rsq_f32_e32 v53, v53
	s_nop 0
	v_mul_f32_e32 v72, 0x45800000, v53
	v_cndmask_b32_e32 v72, v53, v72, vcc
	v_pk_mul_f32 v[54:55], v[72:73], v[54:55] op_sel_hi:[0,1]
	v_pk_mul_f32 v[56:57], v[72:73], v[56:57] op_sel_hi:[0,1]
	v_pk_fma_f32 v[54:55], v[54:55], v[28:29], v[2:3]
	v_pk_fma_f32 v[56:57], v[56:57], v[30:31], v[4:5]
	v_cvt_pk_bf16_f32 v54, v54, v55
	v_cvt_pk_bf16_f32 v55, v56, v57
	global_store_dwordx2 v[70:71], v[54:55], off offset:-1024
	v_pk_mul_f32 v[54:55], v[72:73], v[58:59] op_sel_hi:[0,1]
	v_pk_mul_f32 v[56:57], v[72:73], v[60:61] op_sel_hi:[0,1]
	v_pk_fma_f32 v[54:55], v[54:55], v[32:33], v[6:7]
	v_pk_fma_f32 v[56:57], v[56:57], v[34:35], v[8:9]
	v_cvt_pk_bf16_f32 v54, v54, v55
	v_cvt_pk_bf16_f32 v55, v56, v57
	global_store_dwordx2 v[70:71], v[54:55], off offset:-512
	v_pk_mul_f32 v[54:55], v[72:73], v[62:63] op_sel_hi:[0,1]
	v_pk_mul_f32 v[56:57], v[72:73], v[64:65] op_sel_hi:[0,1]
	v_pk_fma_f32 v[54:55], v[54:55], v[36:37], v[10:11]
	v_pk_fma_f32 v[56:57], v[56:57], v[38:39], v[12:13]
	v_cvt_pk_bf16_f32 v54, v54, v55
	v_cvt_pk_bf16_f32 v55, v56, v57
	global_store_dwordx2 v[70:71], v[54:55], off
	v_pk_mul_f32 v[54:55], v[72:73], v[66:67] op_sel_hi:[0,1]
	v_pk_mul_f32 v[56:57], v[72:73], v[68:69] op_sel_hi:[0,1]
	v_pk_fma_f32 v[54:55], v[54:55], v[40:41], v[14:15]
	v_pk_fma_f32 v[56:57], v[56:57], v[42:43], v[16:17]
	v_cvt_pk_bf16_f32 v54, v54, v55
	v_cvt_pk_bf16_f32 v55, v56, v57
	global_store_dwordx2 v[70:71], v[54:55], off offset:512
	s_cbranch_scc0 .LBB0_120
	s_add_i32 s4, s4, s3
	s_cmpk_gt_i32 s4, 0xff
	s_cbranch_scc0 .LBB0_119

; #define STAGE_A(b, h, kt) do { _Pragma("unroll") for (int i_ = 0; i_ < 2; ++i_) \
;     __builtin_amdgcn_global_load_lds((const unsigned*)((Ab + ((h) * 64 * lda + i_ * 128 * lda + (kt) * 64)) + offA0), (unsigned*)(SA8(b, h) + wid * 1024 + i_ * 8192), 16, 0, 0); } while (0)
; #define STAGE_B(b, h, kt) do { _Pragma("unroll") for (int i_ = 0; i_ < 2; ++i_) \
;     __builtin_amdgcn_global_load_lds((const unsigned*)((Bb + ((h) * 32 * ldb + i_ * 128 * ldb + (kt) * 64)) + offB0), (unsigned*)(SB8(b, h) + wid * 1024 + i_ * 8192), 16, 0, 0); } while (0)
; #define WAIT_V(n) asm volatile("s_waitcnt vmcnt(" #n ")" ::: "memory")
; #define BAR8 __builtin_amdgcn_s_barrier()
; template <bool MID>
; __device__ __forceinline__ void gemm_main8(const int tid, const u16* __restrict__ Ab, int lda, const u16* __restrict__ Bb, int ldb,
;                                            int nkt, char* shm, f32x4 (&acc)[8][4], const u16* __restrict__ midp = nullptr, int tmid = -1) {
;     ...
;   STAGE_B(0, 0, 0); STAGE_A(0, 0, 0); STAGE_B(0, 1, 0); STAGE_A(0, 1, 0);
;   if (wr == 1) BAR8;
;   WAIT_V(4); BAR8;
;   STAGE_B(1, 0, 1); STAGE_A(1, 0, 1); STAGE_B(1, 1, 1);
;   WAIT_V(6); BAR8;
; __device__ __forceinline__ void zero_acc(f32x4 (&acc)[8][4]) {
; #pragma unroll
;   for (int m = 0; m < 8; ++m)
; #pragma unroll
;     for (int n = 0; n < 4; ++n) acc[m][n] = f32x4{0.f, 0.f, 0.f, 0.f};
; }
.LBB0_190:
	v_cndmask_b32_e64 v0, 0, 1, s[0:1]
	s_nop 0
	v_readfirstlane_b32 s0, v0
	s_bitcmp0_b32 s0, 0
	s_mov_b64 s[0:1], -1
	s_cbranch_scc1 .LBB0_185
	s_lshl_b32 s34, s8, 8
	s_ashr_i32 s35, s34, 31
	s_lshl_b32 s92, s21, 8
	s_lshl_b64 s[0:1], s[34:35], 11
	s_add_u32 s18, s15, s0
	s_addc_u32 s19, s36, s1
	s_ashr_i32 s93, s92, 31
	s_lshl_b64 s[6:7], s[92:93], 11
	s_add_u32 s24, s46, s6
	v_readfirstlane_b32 s28, v180
	s_addc_u32 s25, s98, s7
	s_ashr_i32 s8, s28, 6
	s_lshl_b32 s9, s8, 12
	s_lshl_b32 s47, s8, 10
	s_ashr_i32 s10, s28, 8
	v_mov_b32_e32 v0, v182
	v_mov_b32_e32 v2, v181
	s_and_b32 s9, s9, 0x3000
	s_add_i32 vcc_lo, s47, 0x10000
	v_lshl_or_b32 v136, s10, 13, v183
	v_or_b32_e32 v137, s9, v184
	v_lshl_add_u64 v[4:5], v[0:1], 1, s[24:25]
	s_mov_b32 m0, vcc_lo
	s_add_i32 vcc_hi, s47, 0x12000
	global_load_lds_dwordx4 v[4:5], off
	v_lshl_add_u64 v[6:7], v[4:5], 0, s[50:51]
	s_mov_b32 m0, vcc_hi
	v_mov_b32_e32 v3, v1
	global_load_lds_dwordx4 v[6:7], off
	v_lshl_add_u64 v[130:131], v[2:3], 1, s[18:19]
	s_mov_b32 m0, s47
	s_add_i32 s8, s47, 0x2000
	global_load_lds_dwordx4 v[130:131], off
	v_lshl_add_u64 v[6:7], v[130:131], 0, s[50:51]
	s_mov_b32 m0, s8
	s_add_i32 s9, s47, 0x14000
	s_mov_b64 s[16:17], 0x10000
	global_load_lds_dwordx4 v[6:7], off
	v_lshl_add_u64 v[6:7], v[4:5], 0, s[16:17]
	s_mov_b32 m0, s9
	s_mov_b64 s[16:17], 0x50000
	s_add_i32 s37, s47, 0x16000
	global_load_lds_dwordx4 v[6:7], off
	v_lshl_add_u64 v[6:7], v[4:5], 0, s[16:17]
	s_mov_b32 m0, s37
	s_add_i32 s33, s47, 0x4000
	global_load_lds_dwordx4 v[6:7], off
	v_lshl_add_u64 v[6:7], v[130:131], 0, s[56:57]
	s_mov_b32 m0, s33
	s_add_i32 s42, s47, 0x6000
	global_load_lds_dwordx4 v[6:7], off
	v_lshl_add_u64 v[6:7], v[130:131], 0, s[58:59]
	s_mov_b32 m0, s42
	s_cmp_lg_u32 s10, 1
	global_load_lds_dwordx4 v[6:7], off
	v_mov_b32_e32 v14, 0
	v_mov_b32_e32 v15, 0
	v_mov_b32_e32 v16, 0
	v_mov_b32_e32 v17, 0
	v_mov_b32_e32 v22, 0
	v_mov_b32_e32 v23, 0
	v_mov_b32_e32 v24, 0
	v_mov_b32_e32 v25, 0
	v_mov_b32_e32 v10, 0
	v_mov_b32_e32 v11, 0
	v_mov_b32_e32 v12, 0
	v_mov_b32_e32 v13, 0
	v_mov_b32_e32 v18, 0
	v_mov_b32_e32 v19, 0
	v_mov_b32_e32 v20, 0
	v_mov_b32_e32 v21, 0
	v_mov_b32_e32 v30, 0
	v_mov_b32_e32 v31, 0
	v_mov_b32_e32 v32, 0
	v_mov_b32_e32 v33, 0
	v_mov_b32_e32 v38, 0
	v_mov_b32_e32 v39, 0
	v_mov_b32_e32 v40, 0
	v_mov_b32_e32 v41, 0
	v_mov_b32_e32 v26, 0
	v_mov_b32_e32 v27, 0
	v_mov_b32_e32 v28, 0
	v_mov_b32_e32 v29, 0
	v_mov_b32_e32 v34, 0
	v_mov_b32_e32 v35, 0
	v_mov_b32_e32 v36, 0
	v_mov_b32_e32 v37, 0
	v_mov_b32_e32 v46, 0
	v_mov_b32_e32 v47, 0
	v_mov_b32_e32 v48, 0
	v_mov_b32_e32 v49, 0
	v_mov_b32_e32 v54, 0
	v_mov_b32_e32 v55, 0
	v_mov_b32_e32 v56, 0
	v_mov_b32_e32 v57, 0
	v_mov_b32_e32 v42, 0
	v_mov_b32_e32 v43, 0
	v_mov_b32_e32 v44, 0
	v_mov_b32_e32 v45, 0
	v_mov_b32_e32 v50, 0
	v_mov_b32_e32 v51, 0
	v_mov_b32_e32 v52, 0
	v_mov_b32_e32 v53, 0
	v_mov_b32_e32 v58, 0
	v_mov_b32_e32 v59, 0
	v_mov_b32_e32 v60, 0
	v_mov_b32_e32 v61, 0
	v_mov_b32_e32 v62, 0
	v_mov_b32_e32 v63, 0
	v_mov_b32_e32 v64, 0
	v_mov_b32_e32 v65, 0
	v_mov_b32_e32 v66, 0
	v_mov_b32_e32 v67, 0
	v_mov_b32_e32 v68, 0
	v_mov_b32_e32 v69, 0
	v_mov_b32_e32 v70, 0
	v_mov_b32_e32 v71, 0
	v_mov_b32_e32 v72, 0
	v_mov_b32_e32 v73, 0
	v_mov_b32_e32 v82, 0
	v_mov_b32_e32 v83, 0
	v_mov_b32_e32 v84, 0
	v_mov_b32_e32 v85, 0
	v_mov_b32_e32 v86, 0
	v_mov_b32_e32 v87, 0
	v_mov_b32_e32 v88, 0
	v_mov_b32_e32 v89, 0
	v_mov_b32_e32 v74, 0
	v_mov_b32_e32 v75, 0
	v_mov_b32_e32 v76, 0
	v_mov_b32_e32 v77, 0
	v_mov_b32_e32 v78, 0
	v_mov_b32_e32 v79, 0
	v_mov_b32_e32 v80, 0
	v_mov_b32_e32 v81, 0
	v_mov_b32_e32 v98, 0
	v_mov_b32_e32 v99, 0
	v_mov_b32_e32 v100, 0
	v_mov_b32_e32 v101, 0
	v_mov_b32_e32 v102, 0
	v_mov_b32_e32 v103, 0
	v_mov_b32_e32 v104, 0
	v_mov_b32_e32 v105, 0
	v_mov_b32_e32 v90, 0
	v_mov_b32_e32 v91, 0
	v_mov_b32_e32 v92, 0
	v_mov_b32_e32 v93, 0
	v_mov_b32_e32 v94, 0
	v_mov_b32_e32 v95, 0
	v_mov_b32_e32 v96, 0
	v_mov_b32_e32 v97, 0
	v_mov_b32_e32 v114, 0
	v_mov_b32_e32 v115, 0
	v_mov_b32_e32 v116, 0
	v_mov_b32_e32 v117, 0
	v_mov_b32_e32 v118, 0
	v_mov_b32_e32 v119, 0
	v_mov_b32_e32 v120, 0
	v_mov_b32_e32 v121, 0
	v_mov_b32_e32 v106, 0
	v_mov_b32_e32 v107, 0
	v_mov_b32_e32 v108, 0
	v_mov_b32_e32 v109, 0
	v_mov_b32_e32 v110, 0
	v_mov_b32_e32 v111, 0
	v_mov_b32_e32 v112, 0
	v_mov_b32_e32 v113, 0
	v_mov_b32_e32 v122, 0
	v_mov_b32_e32 v123, 0
	v_mov_b32_e32 v124, 0
	v_mov_b32_e32 v125, 0
	v_mov_b32_e32 v126, 0
	v_mov_b32_e32 v127, 0
	v_mov_b32_e32 v128, 0
	v_mov_b32_e32 v129, 0
	s_cbranch_scc1 .LBB0_193
	s_barrier
.LBB0_193:
	s_add_i32 s16, s47, 0x18000
	v_lshl_add_u64 v[4:5], v[4:5], 0, s[60:61]
	s_mov_b32 m0, s16
	s_waitcnt vmcnt(4)
	s_barrier
	global_load_lds_dwordx4 v[4:5], off
	v_lshlrev_b64 v[4:5], 1, v[0:1]
	v_lshl_add_u64 v[6:7], s[24:25], 0, v[4:5]
	s_add_i32 s17, s47, 0x1a000
	v_lshl_add_u64 v[8:9], v[6:7], 0, s[62:63]
	s_mov_b32 m0, s17
	s_add_i32 s24, s47, 0x8000
	global_load_lds_dwordx4 v[8:9], off
	v_lshl_add_u64 v[8:9], v[130:131], 0, s[60:61]
	s_mov_b32 m0, s24
	v_lshlrev_b64 v[2:3], 1, v[2:3]
	global_load_lds_dwordx4 v[8:9], off
	v_lshl_add_u64 v[8:9], s[18:19], 0, v[2:3]
	s_add_i32 s18, s47, 0xa000
	v_lshl_add_u64 v[8:9], v[8:9], 0, s[62:63]
	s_mov_b32 m0, s18
	s_add_i32 s19, s47, 0x1c000
	global_load_lds_dwordx4 v[8:9], off
	v_lshl_add_u64 v[8:9], v[6:7], 0, s[64:65]
	s_mov_b32 m0, s19
	s_add_i32 s25, s47, 0x1e000
	global_load_lds_dwordx4 v[8:9], off
	v_lshl_add_u64 v[6:7], v[6:7], 0, s[66:67]
	s_mov_b32 m0, s25
	s_waitcnt lgkmcnt(0)
	v_lshl_add_u64 v[132:133], s[0:1], 0, v[2:3]
	global_load_lds_dwordx4 v[6:7], off
	s_waitcnt vmcnt(6)
	s_add_u32 s0, s22, s6
	s_addc_u32 s1, s23, s7
	v_mov_b32_e32 v2, 0
	v_lshl_add_u64 v[134:135], s[0:1], 0, v[4:5]
	s_mov_b32 s96, -2
	s_add_i32 s1, s47, 0xc000
	s_add_i32 s0, s47, 0xe000
	s_mov_b64 s[6:7], s[12:13]
	v_mov_b32_e32 v3, v2
	v_mov_b32_e32 v4, v2
	v_mov_b32_e32 v5, v2
	v_mov_b32_e32 v6, v2
	v_mov_b32_e32 v7, v2
	v_mov_b32_e32 v8, v2
	v_mov_b32_e32 v9, v2
	s_barrier

; #define STAGE_A(b, h, kt) do { _Pragma("unroll") for (int i_ = 0; i_ < 2; ++i_) \
;     __builtin_amdgcn_global_load_lds((const unsigned*)((Ab + ((h) * 64 * lda + i_ * 128 * lda + (kt) * 64)) + offA0), (unsigned*)(SA8(b, h) + wid * 1024 + i_ * 8192), 16, 0, 0); } while (0)
; #define STAGE_B(b, h, kt) do { _Pragma("unroll") for (int i_ = 0; i_ < 2; ++i_) \
;     __builtin_amdgcn_global_load_lds((const unsigned*)((Bb + ((h) * 32 * ldb + i_ * 128 * ldb + (kt) * 64)) + offB0), (unsigned*)(SB8(b, h) + wid * 1024 + i_ * 8192), 16, 0, 0); } while (0)
; #define WAIT_V(n) asm volatile("s_waitcnt vmcnt(" #n ")" ::: "memory")
; #define BAR8 __builtin_amdgcn_s_barrier()
; template <bool MID>
; __device__ __forceinline__ void gemm_main8(const int tid, const u16* __restrict__ Ab, int lda, const u16* __restrict__ Bb, int ldb,
;                                            int nkt, char* shm, f32x4 (&acc)[8][4], const u16* __restrict__ midp = nullptr, int tmid = -1) {
;     ...
;   STAGE_B(0, 0, 0); STAGE_A(0, 0, 0); STAGE_B(0, 1, 0); STAGE_A(0, 1, 0);
;   if (wr == 1) BAR8;
;   WAIT_V(4); BAR8;
;   STAGE_B(1, 0, 1); STAGE_A(1, 0, 1); STAGE_B(1, 1, 1);
;   WAIT_V(6); BAR8;
; __device__ __forceinline__ void zero_acc(f32x4 (&acc)[8][4]) {
; #pragma unroll
;   for (int m = 0; m < 8; ++m)
; #pragma unroll
;     for (int n = 0; n < 4; ++n) acc[m][n] = f32x4{0.f, 0.f, 0.f, 0.f};
; }
.LBB0_460:
	v_cndmask_b32_e64 v0, 0, 1, s[0:1]
	s_nop 0
	v_readfirstlane_b32 s0, v0
	s_bitcmp0_b32 s0, 0
	s_mov_b64 s[0:1], -1
	s_cbranch_scc1 .LBB0_455
	s_lshl_b32 s12, s47, 8
	s_ashr_i32 s13, s12, 31
	s_lshl_b32 s14, s14, 8
	s_lshl_b64 s[0:1], s[12:13], 11
	s_add_u32 s24, s33, s0
	s_addc_u32 s25, s36, s1
	s_ashr_i32 s15, s14, 31
	s_lshl_b64 s[18:19], s[14:15], 11
	s_add_u32 s34, s45, s18
	v_readfirstlane_b32 s15, v148
	s_addc_u32 s35, s46, s19
	s_ashr_i32 s16, s15, 6
	s_lshl_b32 s20, s16, 12
	s_lshl_b32 s92, s16, 10
	s_ashr_i32 s17, s15, 8
	v_mov_b32_e32 v0, v161
	v_mov_b32_e32 v2, v160
	s_and_b32 s20, s20, 0x3000
	s_add_i32 s93, s92, 0x10000
	v_lshl_or_b32 v138, s17, 13, v166
	v_or_b32_e32 v139, s20, v155
	v_lshl_add_u64 v[4:5], v[0:1], 1, s[34:35]
	s_mov_b32 m0, s93
	s_add_i32 s98, s92, 0x12000
	global_load_lds_dwordx4 v[4:5], off
	v_lshl_add_u64 v[6:7], v[4:5], 0, s[50:51]
	s_mov_b32 m0, s98
	v_mov_b32_e32 v3, v1
	global_load_lds_dwordx4 v[6:7], off
	v_lshl_add_u64 v[130:131], v[2:3], 1, s[24:25]
	s_mov_b32 m0, s92
	s_add_i32 s99, s92, 0x2000
	global_load_lds_dwordx4 v[130:131], off
	v_lshl_add_u64 v[6:7], v[130:131], 0, s[50:51]
	s_mov_b32 m0, s99
	s_add_i32 vcc_lo, s92, 0x14000
	s_mov_b64 s[20:21], 0x10000
	global_load_lds_dwordx4 v[6:7], off
	v_lshl_add_u64 v[6:7], v[4:5], 0, s[20:21]
	s_mov_b32 m0, vcc_lo
	s_mov_b64 s[20:21], 0x50000
	s_add_i32 vcc_hi, s92, 0x16000
	global_load_lds_dwordx4 v[6:7], off
	v_lshl_add_u64 v[6:7], v[4:5], 0, s[20:21]
	s_mov_b32 m0, vcc_hi
	s_add_i32 s20, s92, 0x4000
	global_load_lds_dwordx4 v[6:7], off
	v_lshl_add_u64 v[6:7], v[130:131], 0, s[56:57]
	s_mov_b32 m0, s20
	s_add_i32 s21, s92, 0x6000
	global_load_lds_dwordx4 v[6:7], off
	v_lshl_add_u64 v[6:7], v[130:131], 0, s[58:59]
	s_mov_b32 m0, s21
	s_cmp_lg_u32 s17, 1
	global_load_lds_dwordx4 v[6:7], off
	v_mov_b32_e32 v14, 0
	v_mov_b32_e32 v15, 0
	v_mov_b32_e32 v16, 0
	v_mov_b32_e32 v17, 0
	v_mov_b32_e32 v22, 0
	v_mov_b32_e32 v23, 0
	v_mov_b32_e32 v24, 0
	v_mov_b32_e32 v25, 0
	v_mov_b32_e32 v10, 0
	v_mov_b32_e32 v11, 0
	v_mov_b32_e32 v12, 0
	v_mov_b32_e32 v13, 0
	v_mov_b32_e32 v18, 0
	v_mov_b32_e32 v19, 0
	v_mov_b32_e32 v20, 0
	v_mov_b32_e32 v21, 0
	v_mov_b32_e32 v30, 0
	v_mov_b32_e32 v31, 0
	v_mov_b32_e32 v32, 0
	v_mov_b32_e32 v33, 0
	v_mov_b32_e32 v38, 0
	v_mov_b32_e32 v39, 0
	v_mov_b32_e32 v40, 0
	v_mov_b32_e32 v41, 0
	v_mov_b32_e32 v26, 0
	v_mov_b32_e32 v27, 0
	v_mov_b32_e32 v28, 0
	v_mov_b32_e32 v29, 0
	v_mov_b32_e32 v34, 0
	v_mov_b32_e32 v35, 0
	v_mov_b32_e32 v36, 0
	v_mov_b32_e32 v37, 0
	v_mov_b32_e32 v46, 0
	v_mov_b32_e32 v47, 0
	v_mov_b32_e32 v48, 0
	v_mov_b32_e32 v49, 0
	v_mov_b32_e32 v54, 0
	v_mov_b32_e32 v55, 0
	v_mov_b32_e32 v56, 0
	v_mov_b32_e32 v57, 0
	v_mov_b32_e32 v42, 0
	v_mov_b32_e32 v43, 0
	v_mov_b32_e32 v44, 0
	v_mov_b32_e32 v45, 0
	v_mov_b32_e32 v50, 0
	v_mov_b32_e32 v51, 0
	v_mov_b32_e32 v52, 0
	v_mov_b32_e32 v53, 0
	v_mov_b32_e32 v58, 0
	v_mov_b32_e32 v59, 0
	v_mov_b32_e32 v60, 0
	v_mov_b32_e32 v61, 0
	v_mov_b32_e32 v62, 0
	v_mov_b32_e32 v63, 0
	v_mov_b32_e32 v64, 0
	v_mov_b32_e32 v65, 0
	v_mov_b32_e32 v66, 0
	v_mov_b32_e32 v67, 0
	v_mov_b32_e32 v68, 0
	v_mov_b32_e32 v69, 0
	v_mov_b32_e32 v70, 0
	v_mov_b32_e32 v71, 0
	v_mov_b32_e32 v72, 0
	v_mov_b32_e32 v73, 0
	v_mov_b32_e32 v82, 0
	v_mov_b32_e32 v83, 0
	v_mov_b32_e32 v84, 0
	v_mov_b32_e32 v85, 0
	v_mov_b32_e32 v86, 0
	v_mov_b32_e32 v87, 0
	v_mov_b32_e32 v88, 0
	v_mov_b32_e32 v89, 0
	v_mov_b32_e32 v74, 0
	v_mov_b32_e32 v75, 0
	v_mov_b32_e32 v76, 0
	v_mov_b32_e32 v77, 0
	v_mov_b32_e32 v78, 0
	v_mov_b32_e32 v79, 0
	v_mov_b32_e32 v80, 0
	v_mov_b32_e32 v81, 0
	v_mov_b32_e32 v98, 0
	v_mov_b32_e32 v99, 0
	v_mov_b32_e32 v100, 0
	v_mov_b32_e32 v101, 0
	v_mov_b32_e32 v102, 0
	v_mov_b32_e32 v103, 0
	v_mov_b32_e32 v104, 0
	v_mov_b32_e32 v105, 0
	v_mov_b32_e32 v90, 0
	v_mov_b32_e32 v91, 0
	v_mov_b32_e32 v92, 0
	v_mov_b32_e32 v93, 0
	v_mov_b32_e32 v94, 0
	v_mov_b32_e32 v95, 0
	v_mov_b32_e32 v96, 0
	v_mov_b32_e32 v97, 0
	v_mov_b32_e32 v114, 0
	v_mov_b32_e32 v115, 0
	v_mov_b32_e32 v116, 0
	v_mov_b32_e32 v117, 0
	v_mov_b32_e32 v118, 0
	v_mov_b32_e32 v119, 0
	v_mov_b32_e32 v120, 0
	v_mov_b32_e32 v121, 0
	v_mov_b32_e32 v106, 0
	v_mov_b32_e32 v107, 0
	v_mov_b32_e32 v108, 0
	v_mov_b32_e32 v109, 0
	v_mov_b32_e32 v110, 0
	v_mov_b32_e32 v111, 0
	v_mov_b32_e32 v112, 0
	v_mov_b32_e32 v113, 0
	v_mov_b32_e32 v122, 0
	v_mov_b32_e32 v123, 0
	v_mov_b32_e32 v124, 0
	v_mov_b32_e32 v125, 0
	v_mov_b32_e32 v126, 0
	v_mov_b32_e32 v127, 0
	v_mov_b32_e32 v128, 0
	v_mov_b32_e32 v129, 0
	s_cbranch_scc1 .LBB0_463
	s_barrier
.LBB0_463:
	s_add_i32 s42, s92, 0x18000
	v_lshl_add_u64 v[4:5], v[4:5], 0, s[60:61]
	s_mov_b32 m0, s42
	s_waitcnt vmcnt(4)
	s_barrier
	global_load_lds_dwordx4 v[4:5], off
	v_lshlrev_b64 v[4:5], 1, v[0:1]
	v_lshl_add_u64 v[6:7], s[34:35], 0, v[4:5]
	s_add_i32 s16, s92, 0x1a000
	v_lshl_add_u64 v[8:9], v[6:7], 0, s[62:63]
	s_mov_b32 m0, s16
	s_add_i32 s17, s92, 0x8000
	global_load_lds_dwordx4 v[8:9], off
	v_lshl_add_u64 v[8:9], v[130:131], 0, s[60:61]
	s_mov_b32 m0, s17
	v_lshlrev_b64 v[2:3], 1, v[2:3]
	global_load_lds_dwordx4 v[8:9], off
	v_lshl_add_u64 v[8:9], s[24:25], 0, v[2:3]
	s_add_i32 s24, s92, 0xa000
	v_lshl_add_u64 v[8:9], v[8:9], 0, s[62:63]
	s_mov_b32 m0, s24
	s_add_i32 s25, s92, 0x1c000
	global_load_lds_dwordx4 v[8:9], off
	v_lshl_add_u64 v[8:9], v[6:7], 0, s[64:65]
	s_mov_b32 m0, s25
	s_add_i32 s34, s92, 0x1e000
	global_load_lds_dwordx4 v[8:9], off
	v_lshl_add_u64 v[6:7], v[6:7], 0, s[66:67]
	s_mov_b32 m0, s34
	v_lshl_add_u64 v[132:133], s[0:1], 0, v[2:3]
	global_load_lds_dwordx4 v[6:7], off
	s_waitcnt vmcnt(6)
	s_add_u32 s0, s22, s18
	s_addc_u32 s1, s23, s19
	v_mov_b32_e32 v2, 0
	v_lshl_add_u64 v[136:137], s[0:1], 0, v[4:5]
	s_mov_b32 s0, -2
	s_mov_b64 s[18:19], s[6:7]
	v_mov_b32_e32 v3, v2
	v_mov_b32_e32 v4, v2
	v_mov_b32_e32 v5, v2
	v_mov_b32_e32 v6, v2
	v_mov_b32_e32 v7, v2
	v_mov_b32_e32 v8, v2
	v_mov_b32_e32 v9, v2
	s_barrier

; #define STAGE_A(b, h, kt) do { _Pragma("unroll") for (int i_ = 0; i_ < 2; ++i_) \
;     __builtin_amdgcn_global_load_lds((const unsigned*)((Ab + ((h) * 64 * lda + i_ * 128 * lda + (kt) * 64)) + offA0), (unsigned*)(SA8(b, h) + wid * 1024 + i_ * 8192), 16, 0, 0); } while (0)
; #define STAGE_B(b, h, kt) do { _Pragma("unroll") for (int i_ = 0; i_ < 2; ++i_) \
;     __builtin_amdgcn_global_load_lds((const unsigned*)((Bb + ((h) * 32 * ldb + i_ * 128 * ldb + (kt) * 64)) + offB0), (unsigned*)(SB8(b, h) + wid * 1024 + i_ * 8192), 16, 0, 0); } while (0)
; #define WAIT_V(n) asm volatile("s_waitcnt vmcnt(" #n ")" ::: "memory")
; #define BAR8 __builtin_amdgcn_s_barrier()
; template <bool MID>
; __device__ __forceinline__ void gemm_main8(const int tid, const u16* __restrict__ Ab, int lda, const u16* __restrict__ Bb, int ldb,
;                                            int nkt, char* shm, f32x4 (&acc)[8][4], const u16* __restrict__ midp = nullptr, int tmid = -1) {
;     ...
;   STAGE_B(0, 0, 0); STAGE_A(0, 0, 0); STAGE_B(0, 1, 0); STAGE_A(0, 1, 0);
;   if (wr == 1) BAR8;
;   WAIT_V(4); BAR8;
;   STAGE_B(1, 0, 1); STAGE_A(1, 0, 1); STAGE_B(1, 1, 1);
;   WAIT_V(6); BAR8;
; __device__ __forceinline__ void zero_acc(f32x4 (&acc)[8][4]) {
; #pragma unroll
;   for (int m = 0; m < 8; ++m)
; #pragma unroll
;     for (int n = 0; n < 4; ++n) acc[m][n] = f32x4{0.f, 0.f, 0.f, 0.f};
; }
.LBB0_601:
	v_cndmask_b32_e64 v0, 0, 1, s[0:1]
	s_nop 0
	v_readfirstlane_b32 s0, v0
	s_bitcmp0_b32 s0, 0
	s_mov_b64 s[0:1], -1
	s_cbranch_scc1 .LBB0_596
	s_lshl_b32 s6, s10, 8
	s_ashr_i32 s7, s6, 31
	s_lshl_b32 s10, s33, 8
	s_lshl_b64 s[0:1], s[6:7], 11
	s_add_u32 s12, s17, s0
	s_addc_u32 s13, s18, s1
	s_ashr_i32 s11, s10, 31
	s_lshl_b64 s[10:11], s[10:11], 11
	s_add_u32 s14, s19, s10
	v_readfirstlane_b32 s34, v140
	s_addc_u32 s15, s24, s11
	s_ashr_i32 s16, s34, 6
	s_lshl_b32 s20, s16, 12
	s_lshl_b32 s35, s16, 10
	s_ashr_i32 s42, s34, 8
	v_mov_b32_e32 v2, v141
	v_mov_b32_e32 v0, v142
	s_and_b32 s20, s20, 0x3000
	s_add_i32 s36, s35, 0x10000
	v_lshl_or_b32 v145, s42, 13, v143
	v_or_b32_e32 v146, s20, v144
	v_lshl_add_u64 v[4:5], v[0:1], 1, s[14:15]
	s_mov_b32 m0, s36
	s_add_i32 s37, s35, 0x12000
	global_load_lds_dwordx4 v[4:5], off
	v_lshl_add_u64 v[6:7], v[4:5], 0, s[50:51]
	s_mov_b32 m0, s37
	v_mov_b32_e32 v3, v1
	global_load_lds_dwordx4 v[6:7], off
	v_lshl_add_u64 v[134:135], v[2:3], 1, s[12:13]
	s_mov_b32 m0, s35
	s_add_i32 s44, s35, 0x2000
	global_load_lds_dwordx4 v[134:135], off
	v_lshl_add_u64 v[6:7], v[134:135], 0, s[50:51]
	s_mov_b32 m0, s44
	s_add_i32 s45, s35, 0x14000
	s_mov_b64 s[20:21], 0x10000
	global_load_lds_dwordx4 v[6:7], off
	v_lshl_add_u64 v[6:7], v[4:5], 0, s[20:21]
	s_mov_b32 m0, s45
	s_mov_b64 s[20:21], 0x50000
	s_add_i32 s46, s35, 0x16000
	global_load_lds_dwordx4 v[6:7], off
	v_lshl_add_u64 v[6:7], v[4:5], 0, s[20:21]
	s_mov_b32 m0, s46
	s_add_i32 s20, s35, 0x4000
	global_load_lds_dwordx4 v[6:7], off
	v_lshl_add_u64 v[6:7], v[134:135], 0, s[56:57]
	s_mov_b32 m0, s20
	s_add_i32 s21, s35, 0x6000
	global_load_lds_dwordx4 v[6:7], off
	v_lshl_add_u64 v[6:7], v[134:135], 0, s[58:59]
	s_mov_b32 m0, s21
	s_cmp_lg_u32 s42, 1
	global_load_lds_dwordx4 v[6:7], off
	v_mov_b32_e32 v14, 0
	v_mov_b32_e32 v15, 0
	v_mov_b32_e32 v16, 0
	v_mov_b32_e32 v17, 0
	v_mov_b32_e32 v22, 0
	v_mov_b32_e32 v23, 0
	v_mov_b32_e32 v24, 0
	v_mov_b32_e32 v25, 0
	v_mov_b32_e32 v10, 0
	v_mov_b32_e32 v11, 0
	v_mov_b32_e32 v12, 0
	v_mov_b32_e32 v13, 0
	v_mov_b32_e32 v18, 0
	v_mov_b32_e32 v19, 0
	v_mov_b32_e32 v20, 0
	v_mov_b32_e32 v21, 0
	v_mov_b32_e32 v30, 0
	v_mov_b32_e32 v31, 0
	v_mov_b32_e32 v32, 0
	v_mov_b32_e32 v33, 0
	v_mov_b32_e32 v38, 0
	v_mov_b32_e32 v39, 0
	v_mov_b32_e32 v40, 0
	v_mov_b32_e32 v41, 0
	v_mov_b32_e32 v26, 0
	v_mov_b32_e32 v27, 0
	v_mov_b32_e32 v28, 0
	v_mov_b32_e32 v29, 0
	v_mov_b32_e32 v34, 0
	v_mov_b32_e32 v35, 0
	v_mov_b32_e32 v36, 0
	v_mov_b32_e32 v37, 0
	v_mov_b32_e32 v46, 0
	v_mov_b32_e32 v47, 0
	v_mov_b32_e32 v48, 0
	v_mov_b32_e32 v49, 0
	v_mov_b32_e32 v54, 0
	v_mov_b32_e32 v55, 0
	v_mov_b32_e32 v56, 0
	v_mov_b32_e32 v57, 0
	v_mov_b32_e32 v42, 0
	v_mov_b32_e32 v43, 0
	v_mov_b32_e32 v44, 0
	v_mov_b32_e32 v45, 0
	v_mov_b32_e32 v50, 0
	v_mov_b32_e32 v51, 0
	v_mov_b32_e32 v52, 0
	v_mov_b32_e32 v53, 0
	v_mov_b32_e32 v58, 0
	v_mov_b32_e32 v59, 0
	v_mov_b32_e32 v60, 0
	v_mov_b32_e32 v61, 0
	v_mov_b32_e32 v62, 0
	v_mov_b32_e32 v63, 0
	v_mov_b32_e32 v64, 0
	v_mov_b32_e32 v65, 0
	v_mov_b32_e32 v66, 0
	v_mov_b32_e32 v67, 0
	v_mov_b32_e32 v68, 0
	v_mov_b32_e32 v69, 0
	v_mov_b32_e32 v70, 0
	v_mov_b32_e32 v71, 0
	v_mov_b32_e32 v72, 0
	v_mov_b32_e32 v73, 0
	v_mov_b32_e32 v82, 0
	v_mov_b32_e32 v83, 0
	v_mov_b32_e32 v84, 0
	v_mov_b32_e32 v85, 0
	v_mov_b32_e32 v86, 0
	v_mov_b32_e32 v87, 0
	v_mov_b32_e32 v88, 0
	v_mov_b32_e32 v89, 0
	v_mov_b32_e32 v74, 0
	v_mov_b32_e32 v75, 0
	v_mov_b32_e32 v76, 0
	v_mov_b32_e32 v77, 0
	v_mov_b32_e32 v78, 0
	v_mov_b32_e32 v79, 0
	v_mov_b32_e32 v80, 0
	v_mov_b32_e32 v81, 0
	v_mov_b32_e32 v98, 0
	v_mov_b32_e32 v99, 0
	v_mov_b32_e32 v100, 0
	v_mov_b32_e32 v101, 0
	v_mov_b32_e32 v102, 0
	v_mov_b32_e32 v103, 0
	v_mov_b32_e32 v104, 0
	v_mov_b32_e32 v105, 0
	v_mov_b32_e32 v90, 0
	v_mov_b32_e32 v91, 0
	v_mov_b32_e32 v92, 0
	v_mov_b32_e32 v93, 0
	v_mov_b32_e32 v94, 0
	v_mov_b32_e32 v95, 0
	v_mov_b32_e32 v96, 0
	v_mov_b32_e32 v97, 0
	v_mov_b32_e32 v114, 0
	v_mov_b32_e32 v115, 0
	v_mov_b32_e32 v116, 0
	v_mov_b32_e32 v117, 0
	v_mov_b32_e32 v118, 0
	v_mov_b32_e32 v119, 0
	v_mov_b32_e32 v120, 0
	v_mov_b32_e32 v121, 0
	v_mov_b32_e32 v106, 0
	v_mov_b32_e32 v107, 0
	v_mov_b32_e32 v108, 0
	v_mov_b32_e32 v109, 0
	v_mov_b32_e32 v110, 0
	v_mov_b32_e32 v111, 0
	v_mov_b32_e32 v112, 0
	v_mov_b32_e32 v113, 0
	v_mov_b32_e32 v122, 0
	v_mov_b32_e32 v123, 0
	v_mov_b32_e32 v124, 0
	v_mov_b32_e32 v125, 0
	v_mov_b32_e32 v126, 0
	v_mov_b32_e32 v127, 0
	v_mov_b32_e32 v128, 0
	v_mov_b32_e32 v129, 0
	s_cbranch_scc1 .LBB0_604
	s_barrier
.LBB0_604:
	s_add_i32 s42, s35, 0x18000
	v_lshl_add_u64 v[4:5], v[4:5], 0, s[60:61]
	s_mov_b32 m0, s42
	s_waitcnt vmcnt(4)
	s_barrier
	global_load_lds_dwordx4 v[4:5], off
	v_lshlrev_b64 v[4:5], 1, v[0:1]
	v_lshl_add_u64 v[6:7], s[14:15], 0, v[4:5]
	s_add_i32 s14, s35, 0x1a000
	v_lshl_add_u64 v[8:9], v[6:7], 0, s[62:63]
	s_mov_b32 m0, s14
	s_add_i32 s15, s35, 0x8000
	global_load_lds_dwordx4 v[8:9], off
	v_lshl_add_u64 v[8:9], v[134:135], 0, s[60:61]
	s_mov_b32 m0, s15
	v_lshlrev_b64 v[2:3], 1, v[2:3]
	global_load_lds_dwordx4 v[8:9], off
	v_lshl_add_u64 v[8:9], s[12:13], 0, v[2:3]
	s_add_i32 s12, s35, 0xa000
	v_lshl_add_u64 v[8:9], v[8:9], 0, s[62:63]
	s_mov_b32 m0, s12
	s_add_i32 s13, s35, 0x1c000
	global_load_lds_dwordx4 v[8:9], off
	v_lshl_add_u64 v[8:9], v[6:7], 0, s[64:65]
	s_mov_b32 m0, s13
	s_add_i32 s16, s35, 0x1e000
	global_load_lds_dwordx4 v[8:9], off
	v_lshl_add_u64 v[6:7], v[6:7], 0, s[66:67]
	s_mov_b32 m0, s16
	v_lshl_add_u64 v[136:137], s[0:1], 0, v[2:3]
	global_load_lds_dwordx4 v[6:7], off
	s_waitcnt vmcnt(6)
	s_add_u32 s0, s22, s10
	s_addc_u32 s1, s23, s11
	v_mov_b32_e32 v2, 0
	v_lshl_add_u64 v[138:139], s[0:1], 0, v[4:5]
	s_mov_b32 s0, -2
	s_mov_b64 s[10:11], s[4:5]
	v_mov_b32_e32 v3, v2
	v_mov_b32_e32 v4, v2
	v_mov_b32_e32 v5, v2
	v_mov_b32_e32 v6, v2
	v_mov_b32_e32 v7, v2
	v_mov_b32_e32 v8, v2
	v_mov_b32_e32 v9, v2
	s_barrier

; #define STAGE_A(b, h, kt) do { _Pragma("unroll") for (int i_ = 0; i_ < 2; ++i_) \
;     __builtin_amdgcn_global_load_lds((const unsigned*)((Ab + ((h) * 64 * lda + i_ * 128 * lda + (kt) * 64)) + offA0), (unsigned*)(SA8(b, h) + wid * 1024 + i_ * 8192), 16, 0, 0); } while (0)
; #define STAGE_B(b, h, kt) do { _Pragma("unroll") for (int i_ = 0; i_ < 2; ++i_) \
;     __builtin_amdgcn_global_load_lds((const unsigned*)((Bb + ((h) * 32 * ldb + i_ * 128 * ldb + (kt) * 64)) + offB0), (unsigned*)(SB8(b, h) + wid * 1024 + i_ * 8192), 16, 0, 0); } while (0)
; #define WAIT_V(n) asm volatile("s_waitcnt vmcnt(" #n ")" ::: "memory")
; #define BAR8 __builtin_amdgcn_s_barrier()
; template <bool MID>
; __device__ __forceinline__ void gemm_main8(const int tid, const u16* __restrict__ Ab, int lda, const u16* __restrict__ Bb, int ldb,
;                                            int nkt, char* shm, f32x4 (&acc)[8][4], const u16* __restrict__ midp = nullptr, int tmid = -1) {
;     ...
;   STAGE_B(0, 0, 0); STAGE_A(0, 0, 0); STAGE_B(0, 1, 0); STAGE_A(0, 1, 0);
;   if (wr == 1) BAR8;
;   WAIT_V(4); BAR8;
;   STAGE_B(1, 0, 1); STAGE_A(1, 0, 1); STAGE_B(1, 1, 1);
;   WAIT_V(6); BAR8;
; __device__ __forceinline__ void zero_acc(f32x4 (&acc)[8][4]) {
; #pragma unroll
;   for (int m = 0; m < 8; ++m)
; #pragma unroll
;     for (int n = 0; n < 4; ++n) acc[m][n] = f32x4{0.f, 0.f, 0.f, 0.f};
; }
.LBB0_676:
	v_cndmask_b32_e64 v0, 0, 1, s[0:1]
	s_nop 0
	v_readfirstlane_b32 s0, v0
	s_bitcmp0_b32 s0, 0
	s_mov_b64 s[0:1], -1
	s_cbranch_scc1 .LBB0_671
	s_lshl_b32 s6, s20, 8
	s_lshl_b32 s21, s8, 8
	s_mul_i32 s0, s20, 0x160000
	s_mul_hi_i32 s1, s6, 0x1600
	s_add_u32 s34, s11, s0
	s_addc_u32 s35, s10, s1
	s_mul_i32 s8, s8, 0x160000
	s_mul_hi_i32 s9, s21, 0x1600
	s_add_u32 s0, s14, s8
	v_readfirstlane_b32 s24, v140
	s_addc_u32 s1, s15, s9
	s_ashr_i32 s7, s24, 6
	s_lshl_b32 s25, s7, 12
	s_and_b32 s25, s25, 0x3000
	v_or_b32_e32 v137, s25, v145
	s_lshl_b32 s25, s7, 10
	s_ashr_i32 s16, s24, 8
	v_mov_b32_e32 v4, v141
	v_mov_b32_e32 v0, v142
	s_add_i32 s28, s25, 0x10000
	v_lshl_or_b32 v136, s16, 13, v143
	v_lshl_add_u64 v[2:3], v[0:1], 1, s[0:1]
	s_mov_b32 m0, s28
	s_mov_b64 s[36:37], 0xb0000
	s_add_i32 s33, s25, 0x12000
	global_load_lds_dwordx4 v[2:3], off
	v_lshl_add_u64 v[6:7], v[2:3], 0, s[36:37]
	s_mov_b32 m0, s33
	v_mov_b32_e32 v5, v1
	global_load_lds_dwordx4 v[6:7], off
	v_lshl_add_u64 v[132:133], v[4:5], 1, s[34:35]
	s_mov_b32 m0, s25
	s_add_i32 s34, s25, 0x2000
	global_load_lds_dwordx4 v[132:133], off
	v_lshl_add_u64 v[4:5], v[132:133], 0, s[36:37]
	s_mov_b32 m0, s34
	s_add_i32 s35, s25, 0x14000
	s_mov_b64 s[36:37], 0x2c000
	global_load_lds_dwordx4 v[4:5], off
	v_lshl_add_u64 v[4:5], v[2:3], 0, s[36:37]
	s_mov_b32 m0, s35
	s_mov_b64 s[36:37], 0xdc000
	global_load_lds_dwordx4 v[4:5], off
	v_lshl_add_u64 v[4:5], v[2:3], 0, s[36:37]
	s_add_i32 s36, s25, 0x16000
	s_mov_b32 m0, s36
	s_add_i32 s37, s25, 0x4000
	s_mov_b64 s[44:45], 0x58000
	global_load_lds_dwordx4 v[4:5], off
	v_lshl_add_u64 v[4:5], v[132:133], 0, s[44:45]
	s_mov_b32 m0, s37
	s_mov_b64 s[44:45], 0x108000
	global_load_lds_dwordx4 v[4:5], off
	v_lshl_add_u64 v[4:5], v[132:133], 0, s[44:45]
	s_add_i32 s44, s25, 0x6000
	s_mov_b32 m0, s44
	s_cmp_lg_u32 s16, 1
	global_load_lds_dwordx4 v[4:5], off
	v_mov_b32_e32 v14, 0
	v_mov_b32_e32 v15, 0
	v_mov_b32_e32 v16, 0
	v_mov_b32_e32 v17, 0
	v_mov_b32_e32 v22, 0
	v_mov_b32_e32 v23, 0
	v_mov_b32_e32 v24, 0
	v_mov_b32_e32 v25, 0
	v_mov_b32_e32 v10, 0
	v_mov_b32_e32 v11, 0
	v_mov_b32_e32 v12, 0
	v_mov_b32_e32 v13, 0
	v_mov_b32_e32 v18, 0
	v_mov_b32_e32 v19, 0
	v_mov_b32_e32 v20, 0
	v_mov_b32_e32 v21, 0
	v_mov_b32_e32 v30, 0
	v_mov_b32_e32 v31, 0
	v_mov_b32_e32 v32, 0
	v_mov_b32_e32 v33, 0
	v_mov_b32_e32 v38, 0
	v_mov_b32_e32 v39, 0
	v_mov_b32_e32 v40, 0
	v_mov_b32_e32 v41, 0
	v_mov_b32_e32 v26, 0
	v_mov_b32_e32 v27, 0
	v_mov_b32_e32 v28, 0
	v_mov_b32_e32 v29, 0
	v_mov_b32_e32 v34, 0
	v_mov_b32_e32 v35, 0
	v_mov_b32_e32 v36, 0
	v_mov_b32_e32 v37, 0
	v_mov_b32_e32 v46, 0
	v_mov_b32_e32 v47, 0
	v_mov_b32_e32 v48, 0
	v_mov_b32_e32 v49, 0
	v_mov_b32_e32 v54, 0
	v_mov_b32_e32 v55, 0
	v_mov_b32_e32 v56, 0
	v_mov_b32_e32 v57, 0
	v_mov_b32_e32 v42, 0
	v_mov_b32_e32 v43, 0
	v_mov_b32_e32 v44, 0
	v_mov_b32_e32 v45, 0
	v_mov_b32_e32 v50, 0
	v_mov_b32_e32 v51, 0
	v_mov_b32_e32 v52, 0
	v_mov_b32_e32 v53, 0
	v_mov_b32_e32 v58, 0
	v_mov_b32_e32 v59, 0
	v_mov_b32_e32 v60, 0
	v_mov_b32_e32 v61, 0
	v_mov_b32_e32 v62, 0
	v_mov_b32_e32 v63, 0
	v_mov_b32_e32 v64, 0
	v_mov_b32_e32 v65, 0
	v_mov_b32_e32 v66, 0
	v_mov_b32_e32 v67, 0
	v_mov_b32_e32 v68, 0
	v_mov_b32_e32 v69, 0
	v_mov_b32_e32 v70, 0
	v_mov_b32_e32 v71, 0
	v_mov_b32_e32 v72, 0
	v_mov_b32_e32 v73, 0
	v_mov_b32_e32 v82, 0
	v_mov_b32_e32 v83, 0
	v_mov_b32_e32 v84, 0
	v_mov_b32_e32 v85, 0
	v_mov_b32_e32 v86, 0
	v_mov_b32_e32 v87, 0
	v_mov_b32_e32 v88, 0
	v_mov_b32_e32 v89, 0
	v_mov_b32_e32 v74, 0
	v_mov_b32_e32 v75, 0
	v_mov_b32_e32 v76, 0
	v_mov_b32_e32 v77, 0
	v_mov_b32_e32 v78, 0
	v_mov_b32_e32 v79, 0
	v_mov_b32_e32 v80, 0
	v_mov_b32_e32 v81, 0
	v_mov_b32_e32 v98, 0
	v_mov_b32_e32 v99, 0
	v_mov_b32_e32 v100, 0
	v_mov_b32_e32 v101, 0
	v_mov_b32_e32 v102, 0
	v_mov_b32_e32 v103, 0
	v_mov_b32_e32 v104, 0
	v_mov_b32_e32 v105, 0
	v_mov_b32_e32 v90, 0
	v_mov_b32_e32 v91, 0
	v_mov_b32_e32 v92, 0
	v_mov_b32_e32 v93, 0
	v_mov_b32_e32 v94, 0
	v_mov_b32_e32 v95, 0
	v_mov_b32_e32 v96, 0
	v_mov_b32_e32 v97, 0
	v_mov_b32_e32 v114, 0
	v_mov_b32_e32 v115, 0
	v_mov_b32_e32 v116, 0
	v_mov_b32_e32 v117, 0
	v_mov_b32_e32 v118, 0
	v_mov_b32_e32 v119, 0
	v_mov_b32_e32 v120, 0
	v_mov_b32_e32 v121, 0
	v_mov_b32_e32 v106, 0
	v_mov_b32_e32 v107, 0
	v_mov_b32_e32 v108, 0
	v_mov_b32_e32 v109, 0
	v_mov_b32_e32 v110, 0
	v_mov_b32_e32 v111, 0
	v_mov_b32_e32 v112, 0
	v_mov_b32_e32 v113, 0
	v_mov_b32_e32 v122, 0
	v_mov_b32_e32 v123, 0
	v_mov_b32_e32 v124, 0
	v_mov_b32_e32 v125, 0
	v_mov_b32_e32 v126, 0
	v_mov_b32_e32 v127, 0
	v_mov_b32_e32 v128, 0
	v_mov_b32_e32 v129, 0
	s_cbranch_scc1 .LBB0_679
	s_barrier
.LBB0_679:
	s_add_i32 s42, s25, 0x18000
	v_lshl_add_u64 v[2:3], v[2:3], 0, s[60:61]
	s_mov_b32 m0, s42
	s_waitcnt vmcnt(4)
	s_barrier
	global_load_lds_dwordx4 v[2:3], off
	v_lshlrev_b64 v[2:3], 1, v[0:1]
	v_lshl_add_u64 v[4:5], s[0:1], 0, v[2:3]
	s_mov_b64 s[46:47], 0xb0080
	s_add_i32 s0, s25, 0x1a000
	v_lshl_add_u64 v[6:7], v[4:5], 0, s[46:47]
	s_mov_b32 m0, s0
	s_add_i32 s1, s25, 0x8000
	global_load_lds_dwordx4 v[6:7], off
	v_lshl_add_u64 v[6:7], v[132:133], 0, s[60:61]
	s_mov_b32 m0, s1
	s_add_i32 s16, s25, 0xa000
	global_load_lds_dwordx4 v[6:7], off
	v_lshl_add_u64 v[6:7], v[132:133], 0, s[46:47]
	s_mov_b32 m0, s16
	s_mov_b64 s[46:47], 0x2c080
	global_load_lds_dwordx4 v[6:7], off
	s_add_i32 s45, s25, 0x1c000
	v_lshl_add_u64 v[6:7], v[4:5], 0, s[46:47]
	s_mov_b64 s[46:47], 0xdc080
	s_mov_b32 m0, s45
	v_lshl_add_u64 v[4:5], v[4:5], 0, s[46:47]
	s_add_i32 s46, s25, 0x1e000
	global_load_lds_dwordx4 v[6:7], off
	s_mov_b32 m0, s46
	s_ashr_i32 s7, s6, 31
	global_load_lds_dwordx4 v[4:5], off
	s_add_u32 s8, s17, s8
	s_waitcnt vmcnt(6)
	s_addc_u32 s9, s18, s9
	v_lshl_add_u64 v[134:135], s[8:9], 0, v[2:3]
	v_mov_b32_e32 v2, 0
	s_mov_b32 s47, -2
	s_mov_b64 s[8:9], 0
	v_mov_b32_e32 v3, v2
	v_mov_b32_e32 v4, v2
	v_mov_b32_e32 v5, v2
	v_mov_b32_e32 v6, v2
	v_mov_b32_e32 v7, v2
	v_mov_b32_e32 v8, v2
	v_mov_b32_e32 v9, v2
	s_barrier
